# P11 output epilogue: the four residual loads of each 16-row group issued together (8 exposed round trips per unit instead of 32 load,wait,store chains)
# baseline (speedup 1.0000x reference)
.LBB0_1470:
	v_mov_b32_e32 v145, v149
	v_mov_b32_e32 v144, v148
	s_lshl_b32 s4, s22, 8
	s_add_i32 s4, s4, s37
	v_add_u32_e32 v144, s4, v144
	s_lshl_b32 s4, s45, 8
	s_ashr_i32 s5, s4, 31
	v_lshlrev_b32_e32 v146, 2, v145
	v_ashrrev_i32_e32 v147, 31, v146
	s_or_b64 s[4:5], s[4:5], s[6:7]
	v_ashrrev_i32_e32 v145, 31, v144
	v_lshl_add_u64 v[146:147], s[4:5], 0, v[146:147]
	v_lshlrev_b64 v[154:155], 10, v[144:145]
	v_lshl_add_u64 v[154:155], v[146:147], 0, v[154:155]
	v_lshl_add_u64 v[156:157], v[154:155], 1, s[8:9]
	global_load_dwordx2 v[158:159], v[156:157], off
	global_load_dwordx2 v[162:163], v[156:157], off offset:32
	global_load_dwordx2 v[164:165], v[156:157], off offset:256
	global_load_dwordx2 v[166:167], v[156:157], off offset:288
	v_lshl_add_u64 v[154:155], v[154:155], 2, s[76:77]
	s_and_b64 vcc, exec, s[0:1]
	s_mov_b64 s[0:1], -1
	s_waitcnt vmcnt(0)
	v_lshlrev_b32_e32 v160, 16, v158
	v_and_b32_e32 v161, 0xffff0000, v158
	v_lshlrev_b32_e32 v158, 16, v159
	v_and_b32_e32 v159, 0xffff0000, v159
	v_pk_fma_f32 v[126:127], v[126:127], 0.5, v[158:159] op_sel_hi:[1,0,1]
	v_pk_fma_f32 v[124:125], v[124:125], 0.5, v[160:161] op_sel_hi:[1,0,1]
	global_store_dwordx4 v[154:155], v[124:127], off
	s_nop 1
	v_lshlrev_b32_e32 v126, 16, v162
	v_and_b32_e32 v127, 0xffff0000, v162
	v_lshlrev_b32_e32 v124, 16, v163
	v_and_b32_e32 v125, 0xffff0000, v163
	v_pk_fma_f32 v[122:123], v[122:123], 0.5, v[124:125] op_sel_hi:[1,0,1]
	v_pk_fma_f32 v[120:121], v[120:121], 0.5, v[126:127] op_sel_hi:[1,0,1]
	global_store_dwordx4 v[154:155], v[120:123], off offset:64
	s_nop 1
	v_lshlrev_b32_e32 v122, 16, v164
	v_and_b32_e32 v123, 0xffff0000, v164
	v_lshlrev_b32_e32 v120, 16, v165
	v_and_b32_e32 v121, 0xffff0000, v165
	v_pk_fma_f32 v[118:119], v[118:119], 0.5, v[120:121] op_sel_hi:[1,0,1]
	v_pk_fma_f32 v[116:117], v[116:117], 0.5, v[122:123] op_sel_hi:[1,0,1]
	global_store_dwordx4 v[154:155], v[116:119], off offset:512
	s_nop 1
	v_lshlrev_b32_e32 v122, 16, v166
	v_add_u32_e32 v118, 16, v144
	v_ashrrev_i32_e32 v119, 31, v118
	v_lshlrev_b64 v[118:119], 10, v[118:119]
	v_and_b32_e32 v123, 0xffff0000, v166
	v_lshlrev_b32_e32 v116, 16, v167
	v_and_b32_e32 v117, 0xffff0000, v167
	v_lshl_add_u64 v[118:119], v[118:119], 0, v[146:147]
	v_pk_fma_f32 v[110:111], v[110:111], 0.5, v[116:117] op_sel_hi:[1,0,1]
	v_pk_fma_f32 v[108:109], v[108:109], 0.5, v[122:123] op_sel_hi:[1,0,1]
	v_lshl_add_u64 v[120:121], v[118:119], 1, s[8:9]
	global_store_dwordx4 v[154:155], v[108:111], off offset:576
	global_load_dwordx2 v[108:109], v[120:121], off
	global_load_dwordx2 v[162:163], v[120:121], off offset:32
	global_load_dwordx2 v[164:165], v[120:121], off offset:256
	global_load_dwordx2 v[166:167], v[120:121], off offset:288
	v_lshl_add_u64 v[116:117], v[118:119], 2, s[76:77]
	s_waitcnt vmcnt(0)
	v_lshlrev_b32_e32 v118, 16, v108
	v_and_b32_e32 v119, 0xffff0000, v108
	v_lshlrev_b32_e32 v108, 16, v109
	v_and_b32_e32 v109, 0xffff0000, v109
	v_pk_fma_f32 v[110:111], v[114:115], 0.5, v[108:109] op_sel_hi:[1,0,1]
	v_pk_fma_f32 v[108:109], v[112:113], 0.5, v[118:119] op_sel_hi:[1,0,1]
	global_store_dwordx4 v[116:117], v[108:111], off
	s_nop 1
	v_lshlrev_b32_e32 v110, 16, v162
	v_and_b32_e32 v111, 0xffff0000, v162
	v_lshlrev_b32_e32 v108, 16, v163
	v_and_b32_e32 v109, 0xffff0000, v163
	v_pk_fma_f32 v[106:107], v[106:107], 0.5, v[108:109] op_sel_hi:[1,0,1]
	v_pk_fma_f32 v[104:105], v[104:105], 0.5, v[110:111] op_sel_hi:[1,0,1]
	global_store_dwordx4 v[116:117], v[104:107], off offset:64
	s_nop 1
	v_lshlrev_b32_e32 v106, 16, v164
	v_and_b32_e32 v107, 0xffff0000, v164
	v_lshlrev_b32_e32 v104, 16, v165
	v_and_b32_e32 v105, 0xffff0000, v165
	v_pk_fma_f32 v[102:103], v[102:103], 0.5, v[104:105] op_sel_hi:[1,0,1]
	v_pk_fma_f32 v[100:101], v[100:101], 0.5, v[106:107] op_sel_hi:[1,0,1]
	global_store_dwordx4 v[116:117], v[100:103], off offset:512
	s_nop 1
	v_lshlrev_b32_e32 v106, 16, v166
	v_add_u32_e32 v102, 32, v144
	v_ashrrev_i32_e32 v103, 31, v102
	v_lshlrev_b64 v[102:103], 10, v[102:103]
	v_and_b32_e32 v107, 0xffff0000, v166
	v_lshlrev_b32_e32 v100, 16, v167
	v_and_b32_e32 v101, 0xffff0000, v167
	v_lshl_add_u64 v[102:103], v[102:103], 0, v[146:147]
	v_pk_fma_f32 v[94:95], v[94:95], 0.5, v[100:101] op_sel_hi:[1,0,1]
	v_pk_fma_f32 v[92:93], v[92:93], 0.5, v[106:107] op_sel_hi:[1,0,1]
	v_lshl_add_u64 v[104:105], v[102:103], 1, s[8:9]
	global_store_dwordx4 v[116:117], v[92:95], off offset:576
	global_load_dwordx2 v[92:93], v[104:105], off
	global_load_dwordx2 v[162:163], v[104:105], off offset:32
	global_load_dwordx2 v[164:165], v[104:105], off offset:256
	global_load_dwordx2 v[166:167], v[104:105], off offset:288
	v_lshl_add_u64 v[100:101], v[102:103], 2, s[76:77]
	s_waitcnt vmcnt(0)
	v_lshlrev_b32_e32 v102, 16, v92
	v_and_b32_e32 v103, 0xffff0000, v92
	v_lshlrev_b32_e32 v92, 16, v93
	v_and_b32_e32 v93, 0xffff0000, v93
	v_pk_fma_f32 v[94:95], v[98:99], 0.5, v[92:93] op_sel_hi:[1,0,1]
	v_pk_fma_f32 v[92:93], v[96:97], 0.5, v[102:103] op_sel_hi:[1,0,1]
	global_store_dwordx4 v[100:101], v[92:95], off
	s_nop 1
	v_lshlrev_b32_e32 v94, 16, v162
	v_and_b32_e32 v95, 0xffff0000, v162
	v_lshlrev_b32_e32 v92, 16, v163
	v_and_b32_e32 v93, 0xffff0000, v163
	v_pk_fma_f32 v[90:91], v[90:91], 0.5, v[92:93] op_sel_hi:[1,0,1]
	v_pk_fma_f32 v[88:89], v[88:89], 0.5, v[94:95] op_sel_hi:[1,0,1]
	global_store_dwordx4 v[100:101], v[88:91], off offset:64
	s_nop 1
	v_lshlrev_b32_e32 v90, 16, v164
	v_and_b32_e32 v91, 0xffff0000, v164
	v_lshlrev_b32_e32 v88, 16, v165
	v_and_b32_e32 v89, 0xffff0000, v165
	v_pk_fma_f32 v[86:87], v[86:87], 0.5, v[88:89] op_sel_hi:[1,0,1]
	v_pk_fma_f32 v[84:85], v[84:85], 0.5, v[90:91] op_sel_hi:[1,0,1]
	global_store_dwordx4 v[100:101], v[84:87], off offset:512
	s_nop 1
	v_lshlrev_b32_e32 v90, 16, v166
	v_add_u32_e32 v86, 48, v144
	v_ashrrev_i32_e32 v87, 31, v86
	v_lshlrev_b64 v[86:87], 10, v[86:87]
	v_and_b32_e32 v91, 0xffff0000, v166
	v_lshlrev_b32_e32 v84, 16, v167
	v_and_b32_e32 v85, 0xffff0000, v167
	v_lshl_add_u64 v[86:87], v[86:87], 0, v[146:147]
	v_pk_fma_f32 v[78:79], v[78:79], 0.5, v[84:85] op_sel_hi:[1,0,1]
	v_pk_fma_f32 v[76:77], v[76:77], 0.5, v[90:91] op_sel_hi:[1,0,1]
	v_lshl_add_u64 v[88:89], v[86:87], 1, s[8:9]
	global_store_dwordx4 v[100:101], v[76:79], off offset:576
	global_load_dwordx2 v[76:77], v[88:89], off
	global_load_dwordx2 v[162:163], v[88:89], off offset:32
	global_load_dwordx2 v[164:165], v[88:89], off offset:256
	global_load_dwordx2 v[166:167], v[88:89], off offset:288
	v_lshl_add_u64 v[84:85], v[86:87], 2, s[76:77]
	s_waitcnt vmcnt(0)
	v_lshlrev_b32_e32 v86, 16, v76
	v_and_b32_e32 v87, 0xffff0000, v76
	v_lshlrev_b32_e32 v76, 16, v77
	v_and_b32_e32 v77, 0xffff0000, v77
	v_pk_fma_f32 v[78:79], v[82:83], 0.5, v[76:77] op_sel_hi:[1,0,1]
	v_pk_fma_f32 v[76:77], v[80:81], 0.5, v[86:87] op_sel_hi:[1,0,1]
	global_store_dwordx4 v[84:85], v[76:79], off
	s_nop 1
	v_lshlrev_b32_e32 v78, 16, v162
	v_and_b32_e32 v79, 0xffff0000, v162
	v_lshlrev_b32_e32 v76, 16, v163
	v_and_b32_e32 v77, 0xffff0000, v163
	v_pk_fma_f32 v[74:75], v[74:75], 0.5, v[76:77] op_sel_hi:[1,0,1]
	v_pk_fma_f32 v[72:73], v[72:73], 0.5, v[78:79] op_sel_hi:[1,0,1]
	global_store_dwordx4 v[84:85], v[72:75], off offset:64
	s_nop 1
	v_lshlrev_b32_e32 v74, 16, v164
	v_and_b32_e32 v75, 0xffff0000, v164
	v_lshlrev_b32_e32 v72, 16, v165
	v_and_b32_e32 v73, 0xffff0000, v165
	v_pk_fma_f32 v[70:71], v[70:71], 0.5, v[72:73] op_sel_hi:[1,0,1]
	v_pk_fma_f32 v[68:69], v[68:69], 0.5, v[74:75] op_sel_hi:[1,0,1]
	global_store_dwordx4 v[84:85], v[68:71], off offset:512
	s_nop 1
	v_lshlrev_b32_e32 v74, 16, v166
	v_add_u32_e32 v70, 0x80, v144
	v_ashrrev_i32_e32 v71, 31, v70
	v_lshlrev_b64 v[70:71], 10, v[70:71]
	v_and_b32_e32 v75, 0xffff0000, v166
	v_lshlrev_b32_e32 v68, 16, v167
	v_and_b32_e32 v69, 0xffff0000, v167
	v_lshl_add_u64 v[70:71], v[70:71], 0, v[146:147]
	v_pk_fma_f32 v[66:67], v[66:67], 0.5, v[68:69] op_sel_hi:[1,0,1]
	v_pk_fma_f32 v[64:65], v[64:65], 0.5, v[74:75] op_sel_hi:[1,0,1]
	v_lshl_add_u64 v[72:73], v[70:71], 1, s[8:9]
	global_store_dwordx4 v[84:85], v[64:67], off offset:576
	global_load_dwordx2 v[64:65], v[72:73], off
	global_load_dwordx2 v[162:163], v[72:73], off offset:32
	global_load_dwordx2 v[164:165], v[72:73], off offset:256
	global_load_dwordx2 v[166:167], v[72:73], off offset:288
	s_waitcnt vmcnt(0)
	v_lshlrev_b32_e32 v68, 16, v64
	v_and_b32_e32 v69, 0xffff0000, v64
	v_lshlrev_b32_e32 v64, 16, v65
	v_and_b32_e32 v65, 0xffff0000, v65
	v_lshl_add_u64 v[66:67], v[70:71], 2, s[76:77]
	v_pk_fma_f32 v[62:63], v[62:63], 0.5, v[64:65] op_sel_hi:[1,0,1]
	v_pk_fma_f32 v[60:61], v[60:61], 0.5, v[68:69] op_sel_hi:[1,0,1]
	global_store_dwordx4 v[66:67], v[60:63], off
	s_nop 1
	v_lshlrev_b32_e32 v62, 16, v162
	v_and_b32_e32 v63, 0xffff0000, v162
	v_lshlrev_b32_e32 v60, 16, v163
	v_and_b32_e32 v61, 0xffff0000, v163
	v_pk_fma_f32 v[58:59], v[58:59], 0.5, v[60:61] op_sel_hi:[1,0,1]
	v_pk_fma_f32 v[56:57], v[56:57], 0.5, v[62:63] op_sel_hi:[1,0,1]
	global_store_dwordx4 v[66:67], v[56:59], off offset:64
	s_nop 1
	v_lshlrev_b32_e32 v58, 16, v164
	v_and_b32_e32 v59, 0xffff0000, v164
	v_lshlrev_b32_e32 v56, 16, v165
	v_and_b32_e32 v57, 0xffff0000, v165
	v_pk_fma_f32 v[54:55], v[54:55], 0.5, v[56:57] op_sel_hi:[1,0,1]
	v_pk_fma_f32 v[52:53], v[52:53], 0.5, v[58:59] op_sel_hi:[1,0,1]
	global_store_dwordx4 v[66:67], v[52:55], off offset:512
	s_nop 1
	v_lshlrev_b32_e32 v58, 16, v166
	v_add_u32_e32 v54, 0x90, v144
	v_ashrrev_i32_e32 v55, 31, v54
	v_lshlrev_b64 v[54:55], 10, v[54:55]
	v_and_b32_e32 v59, 0xffff0000, v166
	v_lshlrev_b32_e32 v52, 16, v167
	v_and_b32_e32 v53, 0xffff0000, v167
	v_lshl_add_u64 v[54:55], v[54:55], 0, v[146:147]
	v_pk_fma_f32 v[46:47], v[46:47], 0.5, v[52:53] op_sel_hi:[1,0,1]
	v_pk_fma_f32 v[44:45], v[44:45], 0.5, v[58:59] op_sel_hi:[1,0,1]
	v_lshl_add_u64 v[56:57], v[54:55], 1, s[8:9]
	global_store_dwordx4 v[66:67], v[44:47], off offset:576
	global_load_dwordx2 v[44:45], v[56:57], off
	global_load_dwordx2 v[162:163], v[56:57], off offset:32
	global_load_dwordx2 v[164:165], v[56:57], off offset:256
	global_load_dwordx2 v[166:167], v[56:57], off offset:288
	v_lshl_add_u64 v[52:53], v[54:55], 2, s[76:77]
	s_waitcnt vmcnt(0)
	v_lshlrev_b32_e32 v54, 16, v44
	v_and_b32_e32 v55, 0xffff0000, v44
	v_lshlrev_b32_e32 v44, 16, v45
	v_and_b32_e32 v45, 0xffff0000, v45
	v_pk_fma_f32 v[46:47], v[50:51], 0.5, v[44:45] op_sel_hi:[1,0,1]
	v_pk_fma_f32 v[44:45], v[48:49], 0.5, v[54:55] op_sel_hi:[1,0,1]
	global_store_dwordx4 v[52:53], v[44:47], off
	s_nop 1
	v_lshlrev_b32_e32 v46, 16, v162
	v_and_b32_e32 v47, 0xffff0000, v162
	v_lshlrev_b32_e32 v44, 16, v163
	v_and_b32_e32 v45, 0xffff0000, v163
	v_pk_fma_f32 v[42:43], v[42:43], 0.5, v[44:45] op_sel_hi:[1,0,1]
	v_pk_fma_f32 v[40:41], v[40:41], 0.5, v[46:47] op_sel_hi:[1,0,1]
	global_store_dwordx4 v[52:53], v[40:43], off offset:64
	s_nop 1
	v_lshlrev_b32_e32 v42, 16, v164
	v_and_b32_e32 v43, 0xffff0000, v164
	v_lshlrev_b32_e32 v40, 16, v165
	v_and_b32_e32 v41, 0xffff0000, v165
	v_pk_fma_f32 v[38:39], v[38:39], 0.5, v[40:41] op_sel_hi:[1,0,1]
	v_pk_fma_f32 v[36:37], v[36:37], 0.5, v[42:43] op_sel_hi:[1,0,1]
	global_store_dwordx4 v[52:53], v[36:39], off offset:512
	s_nop 1
	v_lshlrev_b32_e32 v42, 16, v166
	v_add_u32_e32 v38, 0xa0, v144
	v_ashrrev_i32_e32 v39, 31, v38
	v_lshlrev_b64 v[38:39], 10, v[38:39]
	v_and_b32_e32 v43, 0xffff0000, v166
	v_lshlrev_b32_e32 v36, 16, v167
	v_and_b32_e32 v37, 0xffff0000, v167
	v_lshl_add_u64 v[38:39], v[38:39], 0, v[146:147]
	v_pk_fma_f32 v[30:31], v[30:31], 0.5, v[36:37] op_sel_hi:[1,0,1]
	v_pk_fma_f32 v[28:29], v[28:29], 0.5, v[42:43] op_sel_hi:[1,0,1]
	v_lshl_add_u64 v[40:41], v[38:39], 1, s[8:9]
	global_store_dwordx4 v[52:53], v[28:31], off offset:576
	global_load_dwordx2 v[28:29], v[40:41], off
	global_load_dwordx2 v[162:163], v[40:41], off offset:32
	global_load_dwordx2 v[164:165], v[40:41], off offset:256
	global_load_dwordx2 v[166:167], v[40:41], off offset:288
	v_lshl_add_u64 v[36:37], v[38:39], 2, s[76:77]
	s_waitcnt vmcnt(0)
	v_lshlrev_b32_e32 v38, 16, v28
	v_and_b32_e32 v39, 0xffff0000, v28
	v_lshlrev_b32_e32 v28, 16, v29
	v_and_b32_e32 v29, 0xffff0000, v29
	v_pk_fma_f32 v[30:31], v[34:35], 0.5, v[28:29] op_sel_hi:[1,0,1]
	v_pk_fma_f32 v[28:29], v[32:33], 0.5, v[38:39] op_sel_hi:[1,0,1]
	global_store_dwordx4 v[36:37], v[28:31], off
	s_nop 1
	v_lshlrev_b32_e32 v30, 16, v162
	v_and_b32_e32 v31, 0xffff0000, v162
	v_lshlrev_b32_e32 v28, 16, v163
	v_and_b32_e32 v29, 0xffff0000, v163
	v_pk_fma_f32 v[26:27], v[26:27], 0.5, v[28:29] op_sel_hi:[1,0,1]
	v_pk_fma_f32 v[24:25], v[24:25], 0.5, v[30:31] op_sel_hi:[1,0,1]
	global_store_dwordx4 v[36:37], v[24:27], off offset:64
	s_nop 1
	v_lshlrev_b32_e32 v26, 16, v164
	v_and_b32_e32 v27, 0xffff0000, v164
	v_lshlrev_b32_e32 v24, 16, v165
	v_and_b32_e32 v25, 0xffff0000, v165
	v_pk_fma_f32 v[22:23], v[22:23], 0.5, v[24:25] op_sel_hi:[1,0,1]
	v_pk_fma_f32 v[20:21], v[20:21], 0.5, v[26:27] op_sel_hi:[1,0,1]
	global_store_dwordx4 v[36:37], v[20:23], off offset:512
	s_nop 1
	v_lshlrev_b32_e32 v26, 16, v166
	v_add_u32_e32 v22, 0xb0, v144
	v_ashrrev_i32_e32 v23, 31, v22
	v_lshlrev_b64 v[22:23], 10, v[22:23]
	v_and_b32_e32 v27, 0xffff0000, v166
	v_lshlrev_b32_e32 v20, 16, v167
	v_and_b32_e32 v21, 0xffff0000, v167
	v_lshl_add_u64 v[22:23], v[22:23], 0, v[146:147]
	v_pk_fma_f32 v[14:15], v[14:15], 0.5, v[20:21] op_sel_hi:[1,0,1]
	v_pk_fma_f32 v[12:13], v[12:13], 0.5, v[26:27] op_sel_hi:[1,0,1]
	v_lshl_add_u64 v[24:25], v[22:23], 1, s[8:9]
	global_store_dwordx4 v[36:37], v[12:15], off offset:576
	global_load_dwordx2 v[12:13], v[24:25], off
	global_load_dwordx2 v[162:163], v[24:25], off offset:32
	global_load_dwordx2 v[164:165], v[24:25], off offset:256
	global_load_dwordx2 v[166:167], v[24:25], off offset:288
	v_lshl_add_u64 v[20:21], v[22:23], 2, s[76:77]
	s_waitcnt vmcnt(0)
	v_lshlrev_b32_e32 v22, 16, v12
	v_and_b32_e32 v23, 0xffff0000, v12
	v_lshlrev_b32_e32 v12, 16, v13
	v_and_b32_e32 v13, 0xffff0000, v13
	v_pk_fma_f32 v[14:15], v[18:19], 0.5, v[12:13] op_sel_hi:[1,0,1]
	v_pk_fma_f32 v[12:13], v[16:17], 0.5, v[22:23] op_sel_hi:[1,0,1]
	global_store_dwordx4 v[20:21], v[12:15], off
	s_nop 1
	v_lshlrev_b32_e32 v14, 16, v162
	v_and_b32_e32 v15, 0xffff0000, v162
	v_lshlrev_b32_e32 v12, 16, v163
	v_and_b32_e32 v13, 0xffff0000, v163
	v_pk_fma_f32 v[10:11], v[10:11], 0.5, v[12:13] op_sel_hi:[1,0,1]
	v_pk_fma_f32 v[8:9], v[8:9], 0.5, v[14:15] op_sel_hi:[1,0,1]
	global_store_dwordx4 v[20:21], v[8:11], off offset:64
	s_nop 1
	v_lshlrev_b32_e32 v10, 16, v164
	v_and_b32_e32 v11, 0xffff0000, v164
	v_lshlrev_b32_e32 v8, 16, v165
	v_and_b32_e32 v9, 0xffff0000, v165
	v_pk_fma_f32 v[6:7], v[6:7], 0.5, v[8:9] op_sel_hi:[1,0,1]
	v_pk_fma_f32 v[4:5], v[4:5], 0.5, v[10:11] op_sel_hi:[1,0,1]
	global_store_dwordx4 v[20:21], v[4:7], off offset:512
	s_nop 1
	v_lshlrev_b32_e32 v6, 16, v166
	v_and_b32_e32 v7, 0xffff0000, v166
	v_lshlrev_b32_e32 v4, 16, v167
	v_and_b32_e32 v5, 0xffff0000, v167
	v_pk_fma_f32 v[2:3], v[2:3], 0.5, v[4:5] op_sel_hi:[1,0,1]
	v_pk_fma_f32 v[0:1], v[0:1], 0.5, v[6:7] op_sel_hi:[1,0,1]
	global_store_dwordx4 v[20:21], v[0:3], off offset:576
	s_cbranch_vccnz .LBB0_1457
	s_andn2_b64 vcc, exec, s[10:11]
	s_cbranch_vccnz .LBB0_1456
	s_barrier
	s_branch .LBB0_1456
